# HGRN pass C: the two gate loads (needed only in the output part) moved from the loop top to after the item's first barrier so the first wait covers state + lb only
# speedup vs baseline: 1.0030x; 1.0030x over previous
; #define LAS __attribute__((address_space(3)))
; DI float h2f(unsigned short u) { return (float)__builtin_bit_cast(_Float16, u); }
; DI float flog(float x) { return __builtin_amdgcn_logf(x) * 0.6931471805599453f; }
; DI float sigmoidf_(float x) { return frcp(1.f + fexp(-x)); }
; DI bf16_t* ds_item_ptr(unsigned char* ws, unsigned char* ob, int b, int h, int c) { return (bf16_t*)(b == 0 ? ws + WS_DS0 : ob) + ((size_t)(h * 64 + c)) * 16384; }
; DI void hgC_item(LAS unsigned char* lds, unsigned char* ws, unsigned char* ob, int item, const float* ng, int dummy, const unsigned (&lfr)[16], const unsigned (&qvr)[16], const u32x4 (&ivw)[2], const float* lbp) {
;     ...
;     { const bf16_t* Sg = ds_item_ptr(ws, ob, b, h, c);
; #pragma unroll
;       for (int j = 0; j < 4; ++j) sreg[j] = *(const u32x4*)(Sg + (size_t)(tid + 512 * j) * 8);
; #pragma unroll
;       for (int j = 0; j < 2; ++j) { const int id = tid + 512 * j; gz[j] = *(const u32x4*)(G2 + (size_t)(t0 + (id >> 4)) * DM + h * 128 + (id & 15) * 8); } }
;     float kk0[8], kk1[8], q0v[8], q1v[8], cs0[8], cs1[8];
;     {
;         const f32x2 lb2 = *(const f32x2*)(lbp + h * 128 + 2 * kp);
;         float run0 = 0.f, run1 = 0.f;
; #pragma unroll
;         for (int i = 0; i < 8; ++i) {
;             const float om0 = (1.f - lb2[0]) * sigmoidf_(-h2f((unsigned short)(lfr[i] & 0xffffu)));
;             const float om1 = (1.f - lb2[1]) * sigmoidf_(-h2f((unsigned short)(lfr[i] >> 16)));
;             kk0[i] = om0; kk1[i] = om1;
;             run0 += flog(1.f - om0); run1 += flog(1.f - om1);
;             cs0[i] = run0; cs1[i] = run1;
;             q0v[i] = bflo(qvr[i]); q1v[i] = bfhi(qvr[i]);
;         }
;         *(LAS f32x2*)(tot + tq * 128 + 2 * kp) = (f32x2){run0, run1};
;     }
;     hg_iv_store(VTs, ivw);
; #pragma unroll
;     for (int j = 0; j < 4; ++j) { const int id = tid + 512 * j; *(LAS u32x4*)(SS + (id >> 4) * HROW + (id & 15) * 16) = sreg[j]; }
;     __syncthreads();
.LBB0_1116:
	s_and_b32 s56, s68, 63
	s_lshl_b32 s57, s56, 6
	s_bfe_u32 s91, s68, 0x40006
	s_or_b32 s33, s90, s57
	s_and_b32 s75, s97, 3
	s_cmpk_lt_u32 s68, 0x400
	s_cselect_b32 s57, s95, s81
	s_cselect_b32 s68, s94, s80
	s_lshl_b32 s56, s56, 15
	s_lshl_b32 s90, s91, 21
	s_or_b32 s56, s90, s56
	s_add_u32 s56, s68, s56
	s_addc_u32 s57, s57, 0
	v_lshl_add_u64 v[20:21], s[56:57], 0, v[80:81]
	v_add_co_u32_e32 v12, vcc, s3, v20
	global_load_dwordx4 v[8:11], v80, s[56:57]
	s_nop 0
	v_addc_co_u32_e32 v13, vcc, 0, v21, vcc
	s_movk_i32 s56, 0x4000
	v_add_co_u32_e32 v16, vcc, s56, v20
	v_or_b32_e32 v42, s33, v101
	v_add_u32_e32 v44, s33, v102
	v_addc_co_u32_e32 v17, vcc, 0, v21, vcc
	s_movk_i32 s56, 0x6000
	s_lshl_b32 s68, s91, 8
	v_ashrrev_i32_e32 v43, 31, v42
	v_ashrrev_i32_e32 v45, 31, v44
	v_add_co_u32_e32 v20, vcc, s56, v20
	v_lshl_add_u64 v[40:41], v[84:85], 0, s[68:69]
	v_lshlrev_b64 v[96:97], 12, v[42:43]
	v_lshlrev_b64 v[94:95], 12, v[44:45]
	s_lshl_b32 s68, s91, 9
	v_addc_co_u32_e32 v21, vcc, 0, v21, vcc
	v_lshl_add_u64 v[42:43], v[40:41], 0, v[96:97]
	v_lshl_add_u64 v[40:41], v[40:41], 0, v[94:95]
	v_cvt_f32_f16_e32 v54, v48
	v_cvt_f32_f16_sdwa v55, v48 dst_sel:DWORD dst_unused:UNUSED_PAD src0_sel:WORD_1
	v_lshl_add_u64 v[48:49], v[86:87], 0, s[68:69]
	global_load_dwordx4 v[12:15], v[12:13], off
	s_nop 0
	global_load_dwordx4 v[16:19], v[16:17], off
	v_mul_f32_e32 v54, 0x3fb8aa3b, v54
	global_load_dwordx4 v[20:23], v[20:21], off
	s_nop 0
	v_exp_f32_e32 v54, v54
	global_load_dwordx2 v[58:59], v[48:49], off
.LBB0_1114:
	v_mul_f32_e32 v55, 0x3fb8aa3b, v55
	v_exp_f32_e32 v55, v55
	v_cvt_f32_f16_e32 v49, v30
	v_add_f32_e32 v48, 1.0, v54
	v_rcp_f32_e32 v60, v48
	v_add_f32_e32 v48, 1.0, v55
	v_rcp_f32_e32 v61, v48
	v_cvt_f32_f16_sdwa v30, v30 dst_sel:DWORD dst_unused:UNUSED_PAD src0_sel:WORD_1
	v_mul_f32_e32 v48, 0x3fb8aa3b, v49
	v_exp_f32_e32 v48, v48
	v_lshlrev_b32_e32 v54, 16, v31
	v_mul_f32_e32 v30, 0x3fb8aa3b, v30
	v_exp_f32_e32 v30, v30
	v_and_b32_e32 v55, 0xffff0000, v31
	v_add_f32_e32 v31, 1.0, v48
	v_rcp_f32_e32 v62, v31
	v_cvt_f32_f16_e32 v31, v28
	v_add_f32_e32 v30, 1.0, v30
	v_rcp_f32_e32 v63, v30
	v_cvt_f32_f16_sdwa v28, v28 dst_sel:DWORD dst_unused:UNUSED_PAD src0_sel:WORD_1
	v_mul_f32_e32 v30, 0x3fb8aa3b, v31
	v_exp_f32_e32 v30, v30
	v_lshlrev_b32_e32 v48, 16, v29
	v_mul_f32_e32 v28, 0x3fb8aa3b, v28
	v_exp_f32_e32 v28, v28
	v_and_b32_e32 v49, 0xffff0000, v29
	v_add_f32_e32 v29, 1.0, v30
	v_rcp_f32_e32 v64, v29
	v_cvt_f32_f16_e32 v29, v26
	v_cvt_f32_f16_sdwa v26, v26 dst_sel:DWORD dst_unused:UNUSED_PAD src0_sel:WORD_1
	v_add_f32_e32 v28, 1.0, v28
	v_rcp_f32_e32 v65, v28
	v_mul_f32_e32 v28, 0x3fb8aa3b, v29
	v_exp_f32_e32 v28, v28
	v_mul_f32_e32 v26, 0x3fb8aa3b, v26
	v_exp_f32_e32 v26, v26
	v_lshlrev_b32_e32 v30, 16, v27
	v_and_b32_e32 v31, 0xffff0000, v27
	v_add_f32_e32 v27, 1.0, v28
	v_rcp_f32_e32 v66, v27
	v_add_f32_e32 v26, 1.0, v26
	v_cvt_f32_f16_e32 v27, v56
	v_rcp_f32_e32 v67, v26
	v_cvt_f32_f16_sdwa v26, v56 dst_sel:DWORD dst_unused:UNUSED_PAD src0_sel:WORD_1
	v_lshlrev_b32_e32 v28, 16, v24
	v_mul_f32_e32 v27, 0x3fb8aa3b, v27
	v_exp_f32_e32 v27, v27
	v_mul_f32_e32 v26, 0x3fb8aa3b, v26
	v_exp_f32_e32 v26, v26
	v_and_b32_e32 v29, 0xffff0000, v24
	v_add_f32_e32 v24, 1.0, v27
	v_rcp_f32_e32 v56, v24
	v_add_f32_e32 v24, 1.0, v26
	v_rcp_f32_e32 v57, v24
	v_cvt_f32_f16_sdwa v24, v52 dst_sel:DWORD dst_unused:UNUSED_PAD src0_sel:WORD_1
	v_cvt_f32_f16_e32 v27, v52
	v_cvt_f32_f16_e32 v68, v25
	v_lshlrev_b32_e32 v26, 16, v53
	v_mul_f32_e32 v24, 0x3fb8aa3b, v24
	v_exp_f32_e32 v24, v24
	v_mul_f32_e32 v27, 0x3fb8aa3b, v27
	v_exp_f32_e32 v52, v27
	v_and_b32_e32 v27, 0xffff0000, v53
	v_add_f32_e32 v24, 1.0, v24
	v_rcp_f32_e32 v53, v24
	v_mul_f32_e32 v24, 0x3fb8aa3b, v68
	v_exp_f32_e32 v68, v24
	v_cvt_f32_f16_sdwa v69, v25 dst_sel:DWORD dst_unused:UNUSED_PAD src0_sel:WORD_1
	v_lshlrev_b32_e32 v24, 16, v51
	v_and_b32_e32 v25, 0xffff0000, v51
	v_add_f32_e32 v51, 1.0, v68
	v_mul_f32_e32 v68, 0x3fb8aa3b, v69
	v_exp_f32_e32 v69, v68
	v_cvt_f32_f16_e32 v72, v50
	v_cvt_f32_f16_sdwa v50, v50 dst_sel:DWORD dst_unused:UNUSED_PAD src0_sel:WORD_1
	v_rcp_f32_e32 v68, v51
	v_add_f32_e32 v51, 1.0, v69
	v_mul_f32_e32 v69, 0x3fb8aa3b, v72
	v_mul_f32_e32 v50, 0x3fb8aa3b, v50
	v_exp_f32_e32 v72, v69
	v_exp_f32_e32 v73, v50
	ds_write_b128 v115, v[4:7] offset:52224
	s_waitcnt vmcnt(0)
	v_pk_add_f32 v[4:5], v[58:59], 1.0 op_sel_hi:[1,0] neg_lo:[1,0] neg_hi:[1,0]
	v_rcp_f32_e32 v69, v51
	v_add_f32_e32 v50, 1.0, v72
	v_add_f32_e32 v51, 1.0, v73
	v_pk_mul_f32 v[72:73], v[4:5], v[60:61]
	v_pk_mul_f32 v[74:75], v[4:5], v[62:63]
	v_sub_f32_e32 v6, 1.0, v72
	v_sub_f32_e32 v7, 1.0, v73
	v_log_f32_e32 v6, v6
	v_log_f32_e32 v7, v7
	v_sub_f32_e32 v58, 1.0, v74
	v_sub_f32_e32 v59, 1.0, v75
	v_log_f32_e32 v58, v58
	v_log_f32_e32 v59, v59
	v_add_f32_e32 v52, 1.0, v52
	v_pk_mul_f32 v[64:65], v[4:5], v[64:65]
	v_rcp_f32_e32 v52, v52
	v_sub_f32_e32 v60, 1.0, v64
	v_log_f32_e32 v62, v60
	v_sub_f32_e32 v60, 1.0, v65
	v_pk_fma_f32 v[76:77], v[6:7], s[72:73], 0 op_sel_hi:[1,0,0]
	v_log_f32_e32 v63, v60
	v_pk_fma_f32 v[78:79], v[58:59], s[72:73], v[76:77] op_sel_hi:[1,0,1]
	v_pk_mul_f32 v[58:59], v[4:5], v[56:57]
	v_pk_mul_f32 v[52:53], v[4:5], v[52:53]
	v_sub_f32_e32 v6, 1.0, v58
	v_log_f32_e32 v56, v6
	v_sub_f32_e32 v6, 1.0, v59
	v_rcp_f32_e32 v50, v50
	v_rcp_f32_e32 v51, v51
	v_pk_mul_f32 v[60:61], v[4:5], v[66:67]
	v_log_f32_e32 v57, v6
	v_sub_f32_e32 v6, 1.0, v52
	v_sub_f32_e32 v66, 1.0, v60
	v_sub_f32_e32 v67, 1.0, v61
	v_pk_fma_f32 v[136:137], v[62:63], s[72:73], v[78:79] op_sel_hi:[1,0,1]
	v_log_f32_e32 v62, v6
	v_sub_f32_e32 v6, 1.0, v53
	v_log_f32_e32 v66, v66
	v_log_f32_e32 v67, v67
	v_log_f32_e32 v63, v6
	v_pk_mul_f32 v[6:7], v[4:5], v[68:69]
	v_pk_mul_f32 v[4:5], v[4:5], v[50:51]
	v_sub_f32_e32 v68, 1.0, v6
	v_log_f32_e32 v138, v68
	v_sub_f32_e32 v68, 1.0, v7
	v_log_f32_e32 v139, v68
	v_sub_f32_e32 v50, 1.0, v4
	v_sub_f32_e32 v51, 1.0, v5
	v_pk_fma_f32 v[66:67], v[66:67], s[72:73], v[136:137] op_sel_hi:[1,0,1]
	v_log_f32_e32 v50, v50
	v_log_f32_e32 v51, v51
	v_pk_fma_f32 v[68:69], v[56:57], s[72:73], v[66:67] op_sel_hi:[1,0,1]
	s_ashr_i32 s90, s97, 2
	v_pk_fma_f32 v[62:63], v[62:63], s[72:73], v[68:69] op_sel_hi:[1,0,1]
	s_lshl_b32 s68, s90, 5
	v_pk_fma_f32 v[56:57], v[138:139], s[72:73], v[62:63] op_sel_hi:[1,0,1]
	s_cmp_lt_i32 s90, 0
	v_pk_fma_f32 v[50:51], v[50:51], s[72:73], v[56:57] op_sel_hi:[1,0,1]
	ds_write_b64 v104, v[50:51]
	ds_write_b128 v116, v[0:3] offset:52224
	v_add_u32_e32 v0, v105, v106
	v_add_u32_e32 v1, v105, v107
	ds_write_b128 v0, v[8:11]
	ds_write_b128 v1, v[12:15]
	ds_write_b128 v0, v[16:19] offset:17408
	ds_write_b128 v117, v[20:23]
	s_waitcnt lgkmcnt(0)
	s_barrier
; DI void hgC_load(unsigned char* ws, int item, unsigned (&lf)[16], unsigned (&qv)[16], u32x4 (&ivw)[2]) {
;     const int tid = threadIdx.x, b = item >> 10, h = (item >> 6) & 15, c = item & 63, t0 = b * SEQ + c * 64, kp = tid & 63, tq = tid >> 6;
;     const bf16_t* LOGF = (const bf16_t*)(ws + WS_LOGF);
;     const bf16_t* Q2 = (const bf16_t*)(ws + WS_Q2);
; #pragma unroll
;     for (int i = 0; i < 8; ++i) { const size_t o = (size_t)(t0 + tq * 8 + i) * DM + h * 128 + 2 * kp; lf[i] = *(const unsigned*)(LOGF + o); qv[i] = *(const unsigned*)(Q2 + o); }
;     hg_iv_load((const bf16_t*)(ws + WS_IV), item, ivw);
; DI void hgC_item(LAS unsigned char* lds, unsigned char* ws, unsigned char* ob, int item, const float* ng, int dummy, const unsigned (&lfr)[16], const unsigned (&qvr)[16], const u32x4 (&ivw)[2], const float* lbp) {
;     ...
;       for (int j = 0; j < 4; ++j) sreg[j] = *(const u32x4*)(Sg + (size_t)(tid + 512 * j) * 8);
; #pragma unroll
;       for (int j = 0; j < 2; ++j) { const int id = tid + 512 * j; gz[j] = *(const u32x4*)(G2 + (size_t)(t0 + (id >> 4)) * DM + h * 128 + (id & 15) * 8); } }
	global_load_dwordx4 v[44:47], v[42:43], off
	s_nop 0
	global_load_dwordx4 v[40:43], v[40:41], off
	s_cselect_b32 s32, 1, 0
	s_and_b64 vcc, exec, s[76:77]
	s_cbranch_vccnz .Lp9_pfskip
	s_lshl_b32 s56, s74, 2
	s_lshl_b32 s57, s74, 6
	s_and_b32 s56, s56, 0xfffff000
	s_and_b32 s57, s57, 0xfc0
	s_or_b32 s56, s56, s57
	v_readlane_b32 s57, v254, 3
	s_nop 0
	s_lshl_b32 s57, s57, 3
	s_add_i32 s56, s56, s57
	s_lshl_b32 s56, s56, 12
	s_lshl_b32 s57, s74, 1
	s_and_b32 s57, s57, 0x780
	s_lshl_b32 s57, s57, 1
	s_add_u32 s56, s56, s57
	s_add_u32 s98, s64, s56
	s_addc_u32 s99, s65, 0
	s_add_u32 s100, s66, s56
	s_addc_u32 s101, s67, 0
	v_lshlrev_b32_e32 v148, 1, v98
	global_load_dword v120, v148, s[98:99]
	global_load_dword v121, v148, s[100:101]
	s_add_u32 s98, s98, 0x1000
	s_addc_u32 s99, s99, 0
	s_add_u32 s100, s100, 0x1000
	s_addc_u32 s101, s101, 0
	global_load_dword v122, v148, s[98:99]
	global_load_dword v123, v148, s[100:101]
	s_add_u32 s98, s98, 0x1000
	s_addc_u32 s99, s99, 0
	s_add_u32 s100, s100, 0x1000
	s_addc_u32 s101, s101, 0
	global_load_dword v124, v148, s[98:99]
	global_load_dword v125, v148, s[100:101]
	s_add_u32 s98, s98, 0x1000
	s_addc_u32 s99, s99, 0
	s_add_u32 s100, s100, 0x1000
	s_addc_u32 s101, s101, 0
	global_load_dword v126, v148, s[98:99]
	global_load_dword v127, v148, s[100:101]
	s_add_u32 s98, s98, 0x1000
	s_addc_u32 s99, s99, 0
	s_add_u32 s100, s100, 0x1000
	s_addc_u32 s101, s101, 0
	global_load_dword v128, v148, s[98:99]
	global_load_dword v129, v148, s[100:101]
	s_add_u32 s98, s98, 0x1000
	s_addc_u32 s99, s99, 0
	s_add_u32 s100, s100, 0x1000
	s_addc_u32 s101, s101, 0
	global_load_dword v130, v148, s[98:99]
	global_load_dword v131, v148, s[100:101]
	s_add_u32 s98, s98, 0x1000
	s_addc_u32 s99, s99, 0
	s_add_u32 s100, s100, 0x1000
	s_addc_u32 s101, s101, 0
	global_load_dword v132, v148, s[98:99]
	global_load_dword v133, v148, s[100:101]
	s_add_u32 s98, s98, 0x1000
	s_addc_u32 s99, s99, 0
	s_add_u32 s100, s100, 0x1000
	s_addc_u32 s101, s101, 0
	global_load_dword v134, v148, s[98:99]
	global_load_dword v135, v148, s[100:101]
	s_mov_b32 s56, s74
	s_ashr_i32 s57, s74, 31
	s_lshl_b64 s[56:57], s[56:57], 14
	v_lshl_add_u64 v[148:149], v[82:83], 0, s[56:57]
	v_add_co_u32_e32 v150, vcc, 0x2000, v148
	s_nop 1
	v_addc_co_u32_e32 v151, vcc, 0, v149, vcc
	global_load_dwordx4 v[32:35], v[148:149], off
	global_load_dwordx4 v[36:39], v[150:151], off
